# dsa_topk rank pass: candidate list read 8 entries per trip with branch-free compare (on top of emit/score-loop changes)
# speedup vs baseline: 1.0070x; 1.0004x over previous
; __device__ __forceinline__ void dsa_topk(const bf16_t* DP, const bf16_t* KIN, int* SEL, LAS unsigned char* lds, int widk) {
;     ...
;             const int nc = (int)misc[q * 4 + 3];
;             if (nc <= 256) {
;                 for (int i = sub; i < nc; i += 128) { const unsigned ki = lst[2 * i], si = lst[2 * i + 1]; int rank = 0;
;                     for (int j = 0; j < nc; ++j) { const unsigned kj = lst[2 * j], sj = lst[2 * j + 1]; rank += (kj > ki || (kj == ki && sj < si)) ? 1 : 0; }
;                     if (rank < kkA) selrow[256 - kkA + rank] = (int)si; }
.LBB0_597:
	v_lshl_add_u32 v2, v4, 3, s79
	ds_read_b64 v[2:3], v2
	v_mov_b32_e32 v5, 0
	s_add_i32 s36, s93, -4
	v_mov_b32_e32 v163, s36
	v_readfirstlane_b32 s1, v0
	s_lshr_b32 s0, s1, 3
	s_cmp_eq_u32 s0, 0
	s_cbranch_scc1 .Lrank_tail
.Lrank_loop8:
	ds_read_b64 v[164:165], v163
	ds_read_b64 v[166:167], v163 offset:8
	ds_read_b64 v[168:169], v163 offset:16
	ds_read_b64 v[170:171], v163 offset:24
	ds_read_b64 v[172:173], v163 offset:32
	ds_read_b64 v[174:175], v163 offset:40
	ds_read_b64 v[176:177], v163 offset:48
	ds_read_b64 v[178:179], v163 offset:56
	s_waitcnt lgkmcnt(0)
	v_cmp_gt_u32_e32 vcc, v164, v2
	v_cmp_eq_u32_e64 s[26:27], v164, v2
	v_cmp_lt_u32_e64 s[34:35], v165, v3
	s_and_b64 s[26:27], s[26:27], s[34:35]
	s_or_b64 vcc, vcc, s[26:27]
	v_addc_co_u32_e32 v5, vcc, 0, v5, vcc
	v_cmp_gt_u32_e32 vcc, v166, v2
	v_cmp_eq_u32_e64 s[26:27], v166, v2
	v_cmp_lt_u32_e64 s[34:35], v167, v3
	s_and_b64 s[26:27], s[26:27], s[34:35]
	s_or_b64 vcc, vcc, s[26:27]
	v_addc_co_u32_e32 v5, vcc, 0, v5, vcc
	v_cmp_gt_u32_e32 vcc, v168, v2
	v_cmp_eq_u32_e64 s[26:27], v168, v2
	v_cmp_lt_u32_e64 s[34:35], v169, v3
	s_and_b64 s[26:27], s[26:27], s[34:35]
	s_or_b64 vcc, vcc, s[26:27]
	v_addc_co_u32_e32 v5, vcc, 0, v5, vcc
	v_cmp_gt_u32_e32 vcc, v170, v2
	v_cmp_eq_u32_e64 s[26:27], v170, v2
	v_cmp_lt_u32_e64 s[34:35], v171, v3
	s_and_b64 s[26:27], s[26:27], s[34:35]
	s_or_b64 vcc, vcc, s[26:27]
	v_addc_co_u32_e32 v5, vcc, 0, v5, vcc
	v_cmp_gt_u32_e32 vcc, v172, v2
	v_cmp_eq_u32_e64 s[26:27], v172, v2
	v_cmp_lt_u32_e64 s[34:35], v173, v3
	s_and_b64 s[26:27], s[26:27], s[34:35]
	s_or_b64 vcc, vcc, s[26:27]
	v_addc_co_u32_e32 v5, vcc, 0, v5, vcc
	v_cmp_gt_u32_e32 vcc, v174, v2
	v_cmp_eq_u32_e64 s[26:27], v174, v2
	v_cmp_lt_u32_e64 s[34:35], v175, v3
	s_and_b64 s[26:27], s[26:27], s[34:35]
	s_or_b64 vcc, vcc, s[26:27]
	v_addc_co_u32_e32 v5, vcc, 0, v5, vcc
	v_cmp_gt_u32_e32 vcc, v176, v2
	v_cmp_eq_u32_e64 s[26:27], v176, v2
	v_cmp_lt_u32_e64 s[34:35], v177, v3
	s_and_b64 s[26:27], s[26:27], s[34:35]
	s_or_b64 vcc, vcc, s[26:27]
	v_addc_co_u32_e32 v5, vcc, 0, v5, vcc
	v_cmp_gt_u32_e32 vcc, v178, v2
	v_cmp_eq_u32_e64 s[26:27], v178, v2
	v_cmp_lt_u32_e64 s[34:35], v179, v3
	s_and_b64 s[26:27], s[26:27], s[34:35]
	s_or_b64 vcc, vcc, s[26:27]
	v_addc_co_u32_e32 v5, vcc, 0, v5, vcc
	v_add_u32_e32 v163, 64, v163
	s_sub_u32 s0, s0, 1
	s_cmp_lg_u32 s0, 0
	s_cbranch_scc1 .Lrank_loop8
.Lrank_tail:
	s_and_b32 s0, s1, 7
	s_cmp_eq_u32 s0, 0
	s_cbranch_scc1 .LBB0_601
.Lrank_loop1:
	ds_read_b64 v[164:165], v163
	s_waitcnt lgkmcnt(0)
	v_cmp_gt_u32_e32 vcc, v164, v2
	v_cmp_eq_u32_e64 s[26:27], v164, v2
	v_cmp_lt_u32_e64 s[34:35], v165, v3
	s_and_b64 s[26:27], s[26:27], s[34:35]
	s_or_b64 vcc, vcc, s[26:27]
	v_addc_co_u32_e32 v5, vcc, 0, v5, vcc
	v_add_u32_e32 v163, 8, v163
	s_sub_u32 s0, s0, 1
	s_cmp_lg_u32 s0, 0
	s_cbranch_scc1 .Lrank_loop1
